# attention work-queue fetch: first of the two per-item workgroup barriers removed (LDS item slot alternates by parity so the fetch can start before slower waves arrive)
# speedup vs baseline: 1.0006x; 1.0006x over previous
; DI void phase3(const Params& p, int l, unsigned char* smem, unsigned char* smem0) {
;     ...
;     while (true) {
;         __syncthreads();
;         if (threadIdx.x == 0) {
;             int code = -1;
;             while (vict < 8) {
;                 const int x = (myx + vict) & 7;
;                 const unsigned idx = atomicAdd(cnt + x, 1u);
;                 if (idx < 256u) { code = x * 256 + (int)idx; break; }
;                 ++vict;
;             }
;             *s_item = code;
;         }
;         __syncthreads();
.LBB0_712:
	v_readlane_b32 s0, v253, 16
	v_readlane_b32 s1, v253, 17
	v_xor_b32_e32 v219, 4, v219
	s_and_saveexec_b64 s[4:5], s[0:1]
	s_cbranch_execz .LBB0_720
	s_mov_b64 s[6:7], 0
	v_mov_b32_e32 v3, v124
	s_branch .LBB0_715
